# P7 epilogue: removed redundant canonicalizing v_max (82) with WAR padding
# speedup vs baseline: 1.0135x; 1.0026x over previous
; __device__ __forceinline__ u32x4 pack8(const f32x4& a, const f32x4& b) { u32x4 w; w.x = cvt_pk_bf16(a[0], a[1]); w.y = cvt_pk_bf16(a[2], a[3]); w.z = cvt_pk_bf16(b[0], b[1]); w.w = cvt_pk_bf16(b[2], b[3]); return w; }
; __device__ __forceinline__ float frsq(float x) { return __builtin_amdgcn_rsqf(x); }
;     __device__ __forceinline__ void operator()(Acc& acc, const Unit& u, int wr, int wc, int fr, int fq) const {
;     ...
; #pragma unroll
;         for (int ai = 0; ai < 2; ++ai)
; #pragma unroll
;             for (int m = 0; m < 4; ++m) { const int row = row0 + ai * HALF + m * 16; const float rstd = (ACT == 0) ? frsq(ssv[ai][m] * (1.0f / D) + EPS) : 1.0f;
; #pragma unroll
;                 for (int bj = 0; bj < 2; ++bj) { f32x4 a = acc[ai][bj][m][0] * rstd, b = acc[ai][bj][m][1] * rstd;
;                     if (ACT == 1) {
; #pragma unroll
;                         for (int i = 0; i < 4; ++i) { const float x = fmaxf(a[i], 0.f), y = fmaxf(b[i], 0.f); a[i] = x * x; b[i] = y * y; } }
;                     *(u32x4*)(O + (size_t)row * ldc + col0 + bj * HALF) = pack8(a, b); }
.LBB0_1091:
	v_mov_b32_e32 v146, v140
	v_mov_b32_e32 v147, v141
	s_lshl_b32 s6, s6, 8
	s_add_i32 s6, s6, s58
	v_add_u32_e32 v146, s6, v146
	s_lshl_b32 s6, s71, 8
	v_max_f32_e32 v122, 0, v122
	s_or_b32 s6, s6, s59
	v_max_f32_e32 v124, 0, v124
	v_max_f32_e32 v120, 0, v120
	v_max_f32_e32 v121, 0, v121
	v_mul_f32_e32 v150, v122, v122
	v_max_f32_e32 v122, v127, v127
	v_lshl_add_u32 v148, v147, 3, s6
	v_ashrrev_i32_e32 v147, 31, v146
	v_mul_f32_e32 v124, v124, v124
	v_mul_f32_e32 v120, v120, v120
	v_max_f32_e32 v125, 0, v125
	v_mul_f32_e32 v121, v121, v121
	v_max_f32_e32 v126, 0, v126
	v_max_f32_e32 v122, 0, v122
	v_max_f32_e32 v123, 0, v123
	v_mul_f32_e32 v125, v125, v125
	v_mul_f32_e32 v126, v126, v126
	v_mul_f32_e32 v127, v122, v122
	v_mul_f32_e32 v151, v123, v123
	v_cvt_pk_bf16_f32 v122, v124, v125
	v_cvt_pk_bf16_f32 v123, v126, v127
	v_cvt_pk_bf16_f32 v124, v120, v121
	v_lshlrev_b64 v[120:121], 13, v[146:147]
	v_ashrrev_i32_e32 v149, 31, v148
	v_lshl_add_u64 v[120:121], s[12:13], 0, v[120:121]
	v_lshl_add_u64 v[120:121], v[148:149], 1, v[120:121]
	v_max_f32_e32 v112, 0, v112
	v_cvt_pk_bf16_f32 v125, v150, v151
	global_store_dwordx4 v[120:121], v[122:125], off
	v_max_f32_e32 v113, 0, v113
	v_max_f32_e32 v114, 0, v114
	v_mul_f32_e32 v122, v112, v112
	v_max_f32_e32 v112, v117, v117
	v_max_f32_e32 v112, 0, v112
	v_mul_f32_e32 v117, v113, v113
	v_max_f32_e32 v113, v118, v118
	v_mul_f32_e32 v118, v114, v114
	v_max_f32_e32 v114, v119, v119
	v_max_f32_e32 v116, 0, v116
	v_mul_f32_e32 v112, v112, v112
	v_max_f32_e32 v113, 0, v113
	v_max_f32_e32 v114, 0, v114
	v_max_f32_e32 v115, 0, v115
	v_mul_f32_e32 v116, v116, v116
	v_mul_f32_e32 v113, v113, v113
	v_mul_f32_e32 v114, v114, v114
	v_mul_f32_e32 v115, v115, v115
	v_cvt_pk_bf16_f32 v112, v116, v112
	v_max_f32_e32 v104, 0, v104
	v_max_f32_e32 v105, 0, v105
	v_max_f32_e32 v106, 0, v106
	v_cvt_pk_bf16_f32 v113, v113, v114
	v_cvt_pk_bf16_f32 v114, v122, v117
	v_cvt_pk_bf16_f32 v115, v118, v115
	global_store_dwordx4 v[120:121], v[112:115], off offset:256
	s_nop 1
	v_mul_f32_e32 v112, v104, v104
	v_max_f32_e32 v104, v109, v109
	v_mul_f32_e32 v109, v105, v105
	v_max_f32_e32 v105, v110, v110
	v_mul_f32_e32 v110, v106, v106
	v_max_f32_e32 v106, v111, v111
	v_max_f32_e32 v104, 0, v104
	v_max_f32_e32 v105, 0, v105
	v_max_f32_e32 v106, 0, v106
	v_max_f32_e32 v107, 0, v107
	v_max_f32_e32 v108, 0, v108
	v_mul_f32_e32 v104, v104, v104
	v_mul_f32_e32 v105, v105, v105
	v_mul_f32_e32 v106, v106, v106
	v_mul_f32_e32 v107, v107, v107
	v_mul_f32_e32 v108, v108, v108
	v_cvt_pk_bf16_f32 v104, v108, v104
	v_cvt_pk_bf16_f32 v105, v105, v106
	v_cvt_pk_bf16_f32 v106, v112, v109
	v_cvt_pk_bf16_f32 v107, v110, v107
	v_add_co_u32_e32 v110, vcc, s64, v120
	s_nop 0
	v_addc_co_u32_e32 v111, vcc, 0, v121, vcc
	v_max_f32_e32 v96, 0, v96
	global_store_dwordx4 v[110:111], v[104:107], off
	v_max_f32_e32 v97, 0, v97
	v_max_f32_e32 v98, 0, v98
	v_mul_f32_e32 v104, v96, v96
	v_max_f32_e32 v96, v101, v101
	v_max_f32_e32 v96, 0, v96
	v_mul_f32_e32 v101, v97, v97
	v_max_f32_e32 v97, v102, v102
	v_mul_f32_e32 v102, v98, v98
	v_max_f32_e32 v98, v103, v103
	v_max_f32_e32 v100, 0, v100
	v_mul_f32_e32 v96, v96, v96
	v_max_f32_e32 v97, 0, v97
	v_max_f32_e32 v98, 0, v98
	v_max_f32_e32 v99, 0, v99
	v_lshl_add_u64 v[108:109], v[120:121], 0, s[18:19]
	v_mul_f32_e32 v100, v100, v100
	v_mul_f32_e32 v97, v97, v97
	v_mul_f32_e32 v98, v98, v98
	v_mul_f32_e32 v99, v99, v99
	v_cvt_pk_bf16_f32 v96, v100, v96
	v_max_f32_e32 v88, 0, v88
	v_max_f32_e32 v89, 0, v89
	v_max_f32_e32 v90, 0, v90
	v_cvt_pk_bf16_f32 v97, v97, v98
	v_cvt_pk_bf16_f32 v98, v104, v101
	v_cvt_pk_bf16_f32 v99, v102, v99
	global_store_dwordx4 v[108:109], v[96:99], off offset:256
	s_nop 1
	v_mul_f32_e32 v96, v88, v88
	v_max_f32_e32 v88, v93, v93
	v_mul_f32_e32 v93, v89, v89
	v_max_f32_e32 v89, v94, v94
	v_mul_f32_e32 v94, v90, v90
	v_max_f32_e32 v90, v95, v95
	v_max_f32_e32 v88, 0, v88
	v_max_f32_e32 v89, 0, v89
	v_max_f32_e32 v90, 0, v90
	v_max_f32_e32 v91, 0, v91
	v_max_f32_e32 v92, 0, v92
	v_mul_f32_e32 v88, v88, v88
	v_mul_f32_e32 v89, v89, v89
	v_mul_f32_e32 v90, v90, v90
	v_mul_f32_e32 v91, v91, v91
	v_mul_f32_e32 v92, v92, v92
	v_cvt_pk_bf16_f32 v88, v92, v88
	v_cvt_pk_bf16_f32 v89, v89, v90
	v_cvt_pk_bf16_f32 v90, v96, v93
	v_cvt_pk_bf16_f32 v91, v94, v91
	v_add_co_u32_e32 v94, vcc, s65, v120
	s_nop 0
	v_addc_co_u32_e32 v95, vcc, 0, v121, vcc
	v_max_f32_e32 v80, 0, v80
	global_store_dwordx4 v[94:95], v[88:91], off
	v_max_f32_e32 v81, 0, v81
	v_max_f32_e32 v82, 0, v82
	v_mul_f32_e32 v88, v80, v80
	v_max_f32_e32 v80, v85, v85
	v_max_f32_e32 v80, 0, v80
	v_mul_f32_e32 v85, v81, v81
	v_max_f32_e32 v81, v86, v86
	v_mul_f32_e32 v86, v82, v82
	v_max_f32_e32 v82, v87, v87
	v_max_f32_e32 v84, 0, v84
	v_mul_f32_e32 v80, v80, v80
	v_max_f32_e32 v81, 0, v81
	v_max_f32_e32 v82, 0, v82
	v_max_f32_e32 v83, 0, v83
	v_lshl_add_u64 v[92:93], v[120:121], 0, s[8:9]
	v_mul_f32_e32 v84, v84, v84
	v_mul_f32_e32 v81, v81, v81
	v_mul_f32_e32 v82, v82, v82
	v_mul_f32_e32 v83, v83, v83
	v_cvt_pk_bf16_f32 v80, v84, v80
	v_max_f32_e32 v72, 0, v72
	v_max_f32_e32 v73, 0, v73
	v_max_f32_e32 v74, 0, v74
	v_cvt_pk_bf16_f32 v81, v81, v82
	v_cvt_pk_bf16_f32 v82, v88, v85
	v_cvt_pk_bf16_f32 v83, v86, v83
	global_store_dwordx4 v[92:93], v[80:83], off offset:256
	s_nop 1
	v_mul_f32_e32 v80, v72, v72
	v_max_f32_e32 v72, v77, v77
	v_mul_f32_e32 v77, v73, v73
	v_max_f32_e32 v73, v78, v78
	v_mul_f32_e32 v78, v74, v74
	v_max_f32_e32 v74, v79, v79
	v_max_f32_e32 v72, 0, v72
	v_max_f32_e32 v73, 0, v73
	v_max_f32_e32 v74, 0, v74
	v_max_f32_e32 v75, 0, v75
	v_max_f32_e32 v76, 0, v76
	v_mul_f32_e32 v72, v72, v72
	v_mul_f32_e32 v73, v73, v73
; __device__ __forceinline__ u32x4 pack8(const f32x4& a, const f32x4& b) { u32x4 w; w.x = cvt_pk_bf16(a[0], a[1]); w.y = cvt_pk_bf16(a[2], a[3]); w.z = cvt_pk_bf16(b[0], b[1]); w.w = cvt_pk_bf16(b[2], b[3]); return w; }
; __device__ __forceinline__ float frsq(float x) { return __builtin_amdgcn_rsqf(x); }
;     __device__ __forceinline__ void operator()(Acc& acc, const Unit& u, int wr, int wc, int fr, int fq) const {
;     ...
; #pragma unroll
;         for (int ai = 0; ai < 2; ++ai)
; #pragma unroll
;             for (int m = 0; m < 4; ++m) { const int row = row0 + ai * HALF + m * 16; const float rstd = (ACT == 0) ? frsq(ssv[ai][m] * (1.0f / D) + EPS) : 1.0f;
; #pragma unroll
;                 for (int bj = 0; bj < 2; ++bj) { f32x4 a = acc[ai][bj][m][0] * rstd, b = acc[ai][bj][m][1] * rstd;
;                     if (ACT == 1) {
; #pragma unroll
;                         for (int i = 0; i < 4; ++i) { const float x = fmaxf(a[i], 0.f), y = fmaxf(b[i], 0.f); a[i] = x * x; b[i] = y * y; } }
;                     *(u32x4*)(O + (size_t)row * ldc + col0 + bj * HALF) = pack8(a, b); }
	v_mul_f32_e32 v74, v74, v74
	v_mul_f32_e32 v75, v75, v75
	v_mul_f32_e32 v76, v76, v76
	v_cvt_pk_bf16_f32 v72, v76, v72
	v_cvt_pk_bf16_f32 v73, v73, v74
	v_cvt_pk_bf16_f32 v74, v80, v77
	v_cvt_pk_bf16_f32 v75, v78, v75
	v_add_co_u32_e32 v78, vcc, s66, v120
	s_nop 0
	v_addc_co_u32_e32 v79, vcc, 0, v121, vcc
	v_max_f32_e32 v64, 0, v64
	global_store_dwordx4 v[78:79], v[72:75], off
	v_max_f32_e32 v65, 0, v65
	v_max_f32_e32 v66, 0, v66
	v_mul_f32_e32 v72, v64, v64
	v_max_f32_e32 v64, v69, v69
	v_max_f32_e32 v64, 0, v64
	v_mul_f32_e32 v69, v65, v65
	v_max_f32_e32 v65, v70, v70
	v_mul_f32_e32 v70, v66, v66
	v_max_f32_e32 v66, v71, v71
	v_max_f32_e32 v68, 0, v68
	v_mul_f32_e32 v64, v64, v64
	v_max_f32_e32 v65, 0, v65
	v_max_f32_e32 v66, 0, v66
	v_max_f32_e32 v67, 0, v67
	v_lshl_add_u64 v[76:77], v[120:121], 0, s[20:21]
	v_mul_f32_e32 v68, v68, v68
	v_mul_f32_e32 v65, v65, v65
	v_mul_f32_e32 v66, v66, v66
	v_mul_f32_e32 v67, v67, v67
	v_cvt_pk_bf16_f32 v64, v68, v64
	v_max_f32_e32 v56, 0, v56
	v_max_f32_e32 v57, 0, v57
	v_max_f32_e32 v58, 0, v58
	v_cvt_pk_bf16_f32 v65, v65, v66
	v_cvt_pk_bf16_f32 v66, v72, v69
	v_cvt_pk_bf16_f32 v67, v70, v67
	global_store_dwordx4 v[76:77], v[64:67], off offset:256
	s_nop 1
	v_mul_f32_e32 v64, v56, v56
	v_max_f32_e32 v56, v61, v61
	v_mul_f32_e32 v61, v57, v57
	v_max_f32_e32 v57, v62, v62
	v_mul_f32_e32 v62, v58, v58
	v_max_f32_e32 v58, v63, v63
	v_max_f32_e32 v56, 0, v56
	v_max_f32_e32 v57, 0, v57
	v_max_f32_e32 v58, 0, v58
	v_max_f32_e32 v59, 0, v59
	v_max_f32_e32 v60, 0, v60
	v_mul_f32_e32 v56, v56, v56
	v_mul_f32_e32 v57, v57, v57
	v_mul_f32_e32 v58, v58, v58
	v_mul_f32_e32 v59, v59, v59
	v_mul_f32_e32 v60, v60, v60
	v_cvt_pk_bf16_f32 v56, v60, v56
	v_cvt_pk_bf16_f32 v57, v57, v58
	v_cvt_pk_bf16_f32 v58, v64, v61
	v_cvt_pk_bf16_f32 v59, v62, v59
	v_add_co_u32_e32 v62, vcc, s67, v120
	s_nop 0
	v_addc_co_u32_e32 v63, vcc, 0, v121, vcc
	v_max_f32_e32 v48, 0, v48
	global_store_dwordx4 v[62:63], v[56:59], off
	v_max_f32_e32 v49, 0, v49
	v_max_f32_e32 v50, 0, v50
	v_mul_f32_e32 v56, v48, v48
	v_max_f32_e32 v48, v53, v53
	v_max_f32_e32 v48, 0, v48
	v_mul_f32_e32 v53, v49, v49
	v_max_f32_e32 v49, v54, v54
	v_mul_f32_e32 v54, v50, v50
	v_max_f32_e32 v50, v55, v55
	v_max_f32_e32 v52, 0, v52
	v_mul_f32_e32 v48, v48, v48
	v_max_f32_e32 v49, 0, v49
	v_max_f32_e32 v50, 0, v50
	v_max_f32_e32 v51, 0, v51
	v_lshl_add_u64 v[60:61], v[120:121], 0, s[22:23]
	v_mul_f32_e32 v52, v52, v52
	v_mul_f32_e32 v49, v49, v49
	v_mul_f32_e32 v50, v50, v50
	v_mul_f32_e32 v51, v51, v51
	v_cvt_pk_bf16_f32 v48, v52, v48
	v_max_f32_e32 v40, 0, v40
	v_max_f32_e32 v41, 0, v41
	v_max_f32_e32 v42, 0, v42
	v_cvt_pk_bf16_f32 v49, v49, v50
	v_cvt_pk_bf16_f32 v50, v56, v53
	v_cvt_pk_bf16_f32 v51, v54, v51
	global_store_dwordx4 v[60:61], v[48:51], off offset:256
	s_nop 1
	v_mul_f32_e32 v48, v40, v40
	v_max_f32_e32 v40, v45, v45
	v_mul_f32_e32 v45, v41, v41
	v_max_f32_e32 v41, v46, v46
	v_mul_f32_e32 v46, v42, v42
	v_max_f32_e32 v42, v47, v47
	v_max_f32_e32 v40, 0, v40
	v_max_f32_e32 v41, 0, v41
	v_max_f32_e32 v42, 0, v42
	v_max_f32_e32 v43, 0, v43
	v_max_f32_e32 v44, 0, v44
	v_mul_f32_e32 v40, v40, v40
	v_mul_f32_e32 v41, v41, v41
	v_mul_f32_e32 v42, v42, v42
	v_mul_f32_e32 v43, v43, v43
	v_mul_f32_e32 v44, v44, v44
	v_cvt_pk_bf16_f32 v40, v44, v40
	v_cvt_pk_bf16_f32 v41, v41, v42
	v_cvt_pk_bf16_f32 v42, v48, v45
	v_cvt_pk_bf16_f32 v43, v46, v43
	v_add_co_u32_e32 v46, vcc, s68, v120
	s_nop 0
	v_addc_co_u32_e32 v47, vcc, 0, v121, vcc
	v_max_f32_e32 v32, 0, v32
	global_store_dwordx4 v[46:47], v[40:43], off
	v_max_f32_e32 v33, 0, v33
	v_max_f32_e32 v34, 0, v34
	v_mul_f32_e32 v40, v32, v32
	v_max_f32_e32 v32, v37, v37
	v_max_f32_e32 v32, 0, v32
	v_mul_f32_e32 v37, v33, v33
	v_max_f32_e32 v33, v38, v38
	v_mul_f32_e32 v38, v34, v34
; __device__ __forceinline__ u32x4 pack8(const f32x4& a, const f32x4& b) { u32x4 w; w.x = cvt_pk_bf16(a[0], a[1]); w.y = cvt_pk_bf16(a[2], a[3]); w.z = cvt_pk_bf16(b[0], b[1]); w.w = cvt_pk_bf16(b[2], b[3]); return w; }
; __device__ __forceinline__ float frsq(float x) { return __builtin_amdgcn_rsqf(x); }
;     __device__ __forceinline__ void operator()(Acc& acc, const Unit& u, int wr, int wc, int fr, int fq) const {
;     ...
; #pragma unroll
;         for (int ai = 0; ai < 2; ++ai)
; #pragma unroll
;             for (int m = 0; m < 4; ++m) { const int row = row0 + ai * HALF + m * 16; const float rstd = (ACT == 0) ? frsq(ssv[ai][m] * (1.0f / D) + EPS) : 1.0f;
; #pragma unroll
;                 for (int bj = 0; bj < 2; ++bj) { f32x4 a = acc[ai][bj][m][0] * rstd, b = acc[ai][bj][m][1] * rstd;
;                     if (ACT == 1) {
; #pragma unroll
;                         for (int i = 0; i < 4; ++i) { const float x = fmaxf(a[i], 0.f), y = fmaxf(b[i], 0.f); a[i] = x * x; b[i] = y * y; } }
;                     *(u32x4*)(O + (size_t)row * ldc + col0 + bj * HALF) = pack8(a, b); }
	v_max_f32_e32 v34, v39, v39
	v_max_f32_e32 v36, 0, v36
	v_mul_f32_e32 v32, v32, v32
	v_max_f32_e32 v33, 0, v33
	v_max_f32_e32 v34, 0, v34
	v_max_f32_e32 v35, 0, v35
	v_lshl_add_u64 v[44:45], v[120:121], 0, s[24:25]
	v_mul_f32_e32 v36, v36, v36
	v_mul_f32_e32 v33, v33, v33
	v_mul_f32_e32 v34, v34, v34
	v_mul_f32_e32 v35, v35, v35
	v_cvt_pk_bf16_f32 v32, v36, v32
	v_max_f32_e32 v24, 0, v24
	v_max_f32_e32 v25, 0, v25
	v_max_f32_e32 v26, 0, v26
	v_cvt_pk_bf16_f32 v33, v33, v34
	v_cvt_pk_bf16_f32 v34, v40, v37
	v_cvt_pk_bf16_f32 v35, v38, v35
	global_store_dwordx4 v[44:45], v[32:35], off offset:256
	s_nop 1
	v_mul_f32_e32 v32, v24, v24
	v_max_f32_e32 v24, v29, v29
	v_mul_f32_e32 v29, v25, v25
	v_max_f32_e32 v25, v30, v30
	v_mul_f32_e32 v30, v26, v26
	v_max_f32_e32 v26, v31, v31
	v_max_f32_e32 v24, 0, v24
	v_max_f32_e32 v25, 0, v25
	v_max_f32_e32 v26, 0, v26
	v_max_f32_e32 v27, 0, v27
	v_max_f32_e32 v28, 0, v28
	v_mul_f32_e32 v24, v24, v24
	v_mul_f32_e32 v25, v25, v25
	v_mul_f32_e32 v26, v26, v26
	v_mul_f32_e32 v27, v27, v27
	v_mul_f32_e32 v28, v28, v28
	v_cvt_pk_bf16_f32 v24, v28, v24
	v_cvt_pk_bf16_f32 v25, v25, v26
	v_cvt_pk_bf16_f32 v26, v32, v29
	v_cvt_pk_bf16_f32 v27, v30, v27
	v_add_co_u32_e32 v30, vcc, s69, v120
	s_nop 0
	v_addc_co_u32_e32 v31, vcc, 0, v121, vcc
	v_max_f32_e32 v16, 0, v16
	global_store_dwordx4 v[30:31], v[24:27], off
	v_max_f32_e32 v17, 0, v17
	v_max_f32_e32 v18, 0, v18
	v_mul_f32_e32 v24, v16, v16
	v_max_f32_e32 v16, v21, v21
	v_max_f32_e32 v16, 0, v16
	v_mul_f32_e32 v21, v17, v17
	v_max_f32_e32 v17, v22, v22
	v_mul_f32_e32 v22, v18, v18
	v_max_f32_e32 v18, v23, v23
	v_max_f32_e32 v20, 0, v20
	v_mul_f32_e32 v16, v16, v16
	v_max_f32_e32 v17, 0, v17
	v_max_f32_e32 v18, 0, v18
	v_max_f32_e32 v19, 0, v19
	v_lshl_add_u64 v[28:29], v[120:121], 0, s[26:27]
	v_mul_f32_e32 v20, v20, v20
	v_mul_f32_e32 v17, v17, v17
	v_mul_f32_e32 v18, v18, v18
	v_mul_f32_e32 v19, v19, v19
	v_cvt_pk_bf16_f32 v16, v20, v16
	v_max_f32_e32 v8, 0, v8
	v_max_f32_e32 v9, 0, v9
	v_max_f32_e32 v10, 0, v10
	v_cvt_pk_bf16_f32 v17, v17, v18
	v_cvt_pk_bf16_f32 v18, v24, v21
	v_cvt_pk_bf16_f32 v19, v22, v19
	global_store_dwordx4 v[28:29], v[16:19], off offset:256
	s_nop 1
	v_mul_f32_e32 v16, v8, v8
	v_max_f32_e32 v8, v13, v13
	v_mul_f32_e32 v13, v9, v9
	v_max_f32_e32 v9, v14, v14
	v_mul_f32_e32 v14, v10, v10
	v_max_f32_e32 v10, v15, v15
	v_max_f32_e32 v8, 0, v8
	v_max_f32_e32 v9, 0, v9
	v_max_f32_e32 v10, 0, v10
	v_max_f32_e32 v11, 0, v11
	v_max_f32_e32 v12, 0, v12
	v_mul_f32_e32 v8, v8, v8
	v_mul_f32_e32 v9, v9, v9
	v_mul_f32_e32 v10, v10, v10
	v_mul_f32_e32 v11, v11, v11
	v_mul_f32_e32 v12, v12, v12
	v_cvt_pk_bf16_f32 v8, v12, v8
	v_cvt_pk_bf16_f32 v9, v9, v10
	v_cvt_pk_bf16_f32 v10, v16, v13
	v_cvt_pk_bf16_f32 v11, v14, v11
	v_add_co_u32_e32 v14, vcc, s70, v120
	v_addc_co_u32_e32 v15, vcc, 0, v121, vcc
	v_max_f32_e32 v0, 0, v0
	v_max_f32_e32 v1, 0, v1
	v_max_f32_e32 v2, 0, v2
	global_store_dwordx4 v[14:15], v[8:11], off
	s_nop 1
	v_mul_f32_e32 v8, v0, v0
	v_max_f32_e32 v0, v5, v5
	v_mul_f32_e32 v5, v1, v1
	v_max_f32_e32 v1, v6, v6
	v_mul_f32_e32 v6, v2, v2
	v_max_f32_e32 v2, v7, v7
	v_max_f32_e32 v0, 0, v0
	v_max_f32_e32 v1, 0, v1
	v_max_f32_e32 v2, 0, v2
	v_max_f32_e32 v3, 0, v3
	v_lshl_add_u64 v[12:13], v[120:121], 0, s[28:29]
	v_max_f32_e32 v4, 0, v4
	v_mul_f32_e32 v0, v0, v0
	v_mul_f32_e32 v1, v1, v1
	v_mul_f32_e32 v2, v2, v2
	v_mul_f32_e32 v3, v3, v3
	s_andn2_b64 vcc, exec, s[38:39]
	s_mov_b64 s[38:39], -1
	v_mul_f32_e32 v4, v4, v4
	v_cvt_pk_bf16_f32 v0, v4, v0
	v_cvt_pk_bf16_f32 v1, v1, v2
	v_cvt_pk_bf16_f32 v2, v8, v5
	v_cvt_pk_bf16_f32 v3, v6, v3
	global_store_dwordx4 v[12:13], v[0:3], off offset:256
	s_cbranch_vccnz .LBB0_1084
	s_andn2_b64 vcc, exec, s[10:11]
	s_cbranch_vccnz .LBB0_1083
	s_barrier
	s_branch .LBB0_1083
